# XCD-local barrier: L1 invalidate (buffer_inv sc1) issued right behind the arrival atomic instead of after the release is seen
# baseline (speedup 1.0000x reference)
; __device__ __forceinline__ unsigned xb_ld(unsigned* p)              { return __hip_atomic_load(p, __ATOMIC_RELAXED, __HIP_MEMORY_SCOPE_AGENT); }
; __device__ __forceinline__ unsigned xb_add(unsigned* p, unsigned v) { return __hip_atomic_fetch_add(p, v, __ATOMIC_RELAXED, __HIP_MEMORY_SCOPE_AGENT); }
; #define XB_SPIN(cond, bar) do { unsigned _sp = 0; while (cond) { __builtin_amdgcn_s_sleep(1); \
;     if ((++_sp & 255u) == 0u) { if (xb_ld(&(bar)[XB_TMO])) break; if (_sp > XB_SPIN_CAP) { atomicAdd(&(bar)[XB_TMO], 1u); break; } } } } while (0)
; __device__ __forceinline__ void xcd_barrier_local(const XcdBarrier& b) {
;     ...
;         __builtin_amdgcn_s_waitcnt(0);
;         const unsigned nloc = b.st[0] ? b.st[0] : 1u;
;         const unsigned old = xb_add(&bar[XB_XSUB(b.x)], 1u);
;         const unsigned target = (old / nloc + 1u) * nloc;
;         if (old + 1u == target) (void)xb_add(&bar[XB_XGEN(b.x)], 1u);
;         else XB_SPIN(xb_ld(&bar[XB_XSUB(b.x)]) < target, bar);
.LBB0_859:
	s_or_b64 exec, exec, s[14:15]
	buffer_inv sc1
	s_waitcnt vmcnt(0)
	v_readfirstlane_b32 s4, v2
	s_waitcnt lgkmcnt(0)
	v_cvt_f32_u32_e32 v2, v0
	v_sub_u32_e32 v3, 0, v0
	v_add_u32_e32 v1, s4, v1
	s_mov_b64 s[16:17], 0
	v_rcp_iflag_f32_e32 v2, v2
	s_nop 0
	v_mul_f32_e32 v2, 0x4f7ffffe, v2
	v_cvt_u32_f32_e32 v2, v2
	v_mul_lo_u32 v3, v3, v2
	v_mul_hi_u32 v3, v2, v3
	v_add_u32_e32 v2, v2, v3
	v_mul_hi_u32 v2, v1, v2
	v_mul_lo_u32 v3, v2, v0
	v_sub_u32_e32 v3, v1, v3
	v_cmp_ge_u32_e32 vcc, v3, v0
	v_add_u32_e32 v4, 1, v2
	v_add_u32_e32 v1, 1, v1
	v_cndmask_b32_e32 v2, v2, v4, vcc
	v_sub_u32_e32 v4, v3, v0
	v_cndmask_b32_e32 v3, v3, v4, vcc
	v_cmp_ge_u32_e32 vcc, v3, v0
	v_add_u32_e32 v3, 1, v2
	s_nop 0
	v_cndmask_b32_e32 v2, v2, v3, vcc
	v_mul_lo_u32 v2, v0, v2
	v_add_u32_e32 v0, v2, v0
	v_cmp_ne_u32_e32 vcc, v1, v0
	s_and_saveexec_b64 s[4:5], vcc
	s_xor_b64 s[12:13], exec, s[4:5]
	s_cbranch_execz .LBB0_869
	global_load_dword v1, v201, s[8:9] sc1
	s_mov_b64 s[18:19], 0
	s_waitcnt vmcnt(0)
	v_cmp_lt_u32_e32 vcc, v1, v0
	s_and_saveexec_b64 s[16:17], vcc
	s_cbranch_execz .LBB0_872
	s_add_u32 s14, s2, 0x200
	s_addc_u32 s15, s3, 0
	s_mov_b32 s4, 1
	s_branch .LBB0_863

; __device__ __forceinline__ unsigned xb_ld(unsigned* p)              { return __hip_atomic_load(p, __ATOMIC_RELAXED, __HIP_MEMORY_SCOPE_AGENT); }
; #define XB_SPIN(cond, bar) do { unsigned _sp = 0; while (cond) { __builtin_amdgcn_s_sleep(1); \
;     if ((++_sp & 255u) == 0u) { if (xb_ld(&(bar)[XB_TMO])) break; if (_sp > XB_SPIN_CAP) { atomicAdd(&(bar)[XB_TMO], 1u); break; } } } } while (0)
; __device__ __forceinline__ void xcd_barrier_local(const XcdBarrier& b) {
;     ...
;         else XB_SPIN(xb_ld(&bar[XB_XSUB(b.x)]) < target, bar);
;         __builtin_amdgcn_fence(__ATOMIC_ACQUIRE, "agent");
;         asm volatile("s_waitcnt vmcnt(0)" ::: "memory");
;     }
.LBB0_875:
	s_or_b64 exec, exec, s[2:3]
	s_waitcnt vmcnt(0)
	s_waitcnt vmcnt(0)

; __device__ __forceinline__ unsigned xb_ld(unsigned* p)              { return __hip_atomic_load(p, __ATOMIC_RELAXED, __HIP_MEMORY_SCOPE_AGENT); }
; __device__ __forceinline__ unsigned xb_add(unsigned* p, unsigned v) { return __hip_atomic_fetch_add(p, v, __ATOMIC_RELAXED, __HIP_MEMORY_SCOPE_AGENT); }
; #define XB_SPIN(cond, bar) do { unsigned _sp = 0; while (cond) { __builtin_amdgcn_s_sleep(1); \
;     if ((++_sp & 255u) == 0u) { if (xb_ld(&(bar)[XB_TMO])) break; if (_sp > XB_SPIN_CAP) { atomicAdd(&(bar)[XB_TMO], 1u); break; } } } } while (0)
; __device__ __forceinline__ void xcd_barrier_local(const XcdBarrier& b) {
;     ...
;         __builtin_amdgcn_s_waitcnt(0);
;         const unsigned nloc = b.st[0] ? b.st[0] : 1u;
;         const unsigned old = xb_add(&bar[XB_XSUB(b.x)], 1u);
;         const unsigned target = (old / nloc + 1u) * nloc;
;         if (old + 1u == target) (void)xb_add(&bar[XB_XGEN(b.x)], 1u);
;         else XB_SPIN(xb_ld(&bar[XB_XSUB(b.x)]) < target, bar);
.LBB0_956:
	s_or_b64 exec, exec, s[14:15]
	buffer_inv sc1
	s_waitcnt vmcnt(0)
	v_readfirstlane_b32 s1, v2
	s_waitcnt lgkmcnt(0)
	v_cvt_f32_u32_e32 v2, v0
	v_sub_u32_e32 v3, 0, v0
	v_add_u32_e32 v1, s1, v1
	s_mov_b64 s[16:17], 0
	v_rcp_iflag_f32_e32 v2, v2
	s_nop 0
	v_mul_f32_e32 v2, 0x4f7ffffe, v2
	v_cvt_u32_f32_e32 v2, v2
	v_mul_lo_u32 v3, v3, v2
	v_mul_hi_u32 v3, v2, v3
	v_add_u32_e32 v2, v2, v3
	v_mul_hi_u32 v2, v1, v2
	v_mul_lo_u32 v3, v2, v0
	v_sub_u32_e32 v3, v1, v3
	v_cmp_ge_u32_e32 vcc, v3, v0
	v_add_u32_e32 v4, 1, v2
	v_add_u32_e32 v1, 1, v1
	v_cndmask_b32_e32 v2, v2, v4, vcc
	v_sub_u32_e32 v4, v3, v0
	v_cndmask_b32_e32 v3, v3, v4, vcc
	v_cmp_ge_u32_e32 vcc, v3, v0
	v_add_u32_e32 v3, 1, v2
	s_nop 0
	v_cndmask_b32_e32 v2, v2, v3, vcc
	v_mul_lo_u32 v2, v0, v2
	v_add_u32_e32 v0, v2, v0
	v_cmp_ne_u32_e32 vcc, v1, v0
	s_and_saveexec_b64 s[4:5], vcc
	s_xor_b64 s[12:13], exec, s[4:5]
	s_cbranch_execz .LBB0_966
	global_load_dword v1, v201, s[10:11] sc1
	s_mov_b64 s[18:19], 0
	s_waitcnt vmcnt(0)
	v_cmp_lt_u32_e32 vcc, v1, v0
	s_and_saveexec_b64 s[16:17], vcc
	s_cbranch_execz .LBB0_969
	s_add_u32 s14, s2, 0x200
	s_addc_u32 s15, s3, 0
	s_mov_b32 s1, 1
	s_branch .LBB0_960

; __device__ __forceinline__ unsigned xb_ld(unsigned* p)              { return __hip_atomic_load(p, __ATOMIC_RELAXED, __HIP_MEMORY_SCOPE_AGENT); }
; __device__ __forceinline__ unsigned xb_add(unsigned* p, unsigned v) { return __hip_atomic_fetch_add(p, v, __ATOMIC_RELAXED, __HIP_MEMORY_SCOPE_AGENT); }
; #define XB_SPIN(cond, bar) do { unsigned _sp = 0; while (cond) { __builtin_amdgcn_s_sleep(1); \
;     if ((++_sp & 255u) == 0u) { if (xb_ld(&(bar)[XB_TMO])) break; if (_sp > XB_SPIN_CAP) { atomicAdd(&(bar)[XB_TMO], 1u); break; } } } } while (0)
; __device__ __forceinline__ void xcd_barrier_local(const XcdBarrier& b) {
;     ...
;         __builtin_amdgcn_s_waitcnt(0);
;         const unsigned nloc = b.st[0] ? b.st[0] : 1u;
;         const unsigned old = xb_add(&bar[XB_XSUB(b.x)], 1u);
;         const unsigned target = (old / nloc + 1u) * nloc;
;         if (old + 1u == target) (void)xb_add(&bar[XB_XGEN(b.x)], 1u);
;         else XB_SPIN(xb_ld(&bar[XB_XSUB(b.x)]) < target, bar);
.LBB0_1294:
	s_or_b64 exec, exec, s[10:11]
	buffer_inv sc1
	s_waitcnt vmcnt(0)
	v_readfirstlane_b32 s8, v2
	s_waitcnt lgkmcnt(0)
	v_cvt_f32_u32_e32 v2, v0
	v_sub_u32_e32 v3, 0, v0
	v_add_u32_e32 v1, s8, v1
	s_mov_b64 s[12:13], 0
	v_rcp_iflag_f32_e32 v2, v2
	s_nop 0
	v_mul_f32_e32 v2, 0x4f7ffffe, v2
	v_cvt_u32_f32_e32 v2, v2
	v_mul_lo_u32 v3, v3, v2
	v_mul_hi_u32 v3, v2, v3
	v_add_u32_e32 v2, v2, v3
	v_mul_hi_u32 v2, v1, v2
	v_mul_lo_u32 v3, v2, v0
	v_sub_u32_e32 v3, v1, v3
	v_cmp_ge_u32_e32 vcc, v3, v0
	v_add_u32_e32 v4, 1, v2
	v_add_u32_e32 v1, 1, v1
	v_cndmask_b32_e32 v2, v2, v4, vcc
	v_sub_u32_e32 v4, v3, v0
	v_cndmask_b32_e32 v3, v3, v4, vcc
	v_cmp_ge_u32_e32 vcc, v3, v0
	v_add_u32_e32 v3, 1, v2
	s_nop 0
	v_cndmask_b32_e32 v2, v2, v3, vcc
	v_mul_lo_u32 v2, v0, v2
	v_add_u32_e32 v0, v2, v0
	v_cmp_ne_u32_e32 vcc, v1, v0
	s_and_saveexec_b64 s[8:9], vcc
	s_xor_b64 s[8:9], exec, s[8:9]
	s_cbranch_execz .LBB0_1304
	global_load_dword v1, v201, s[6:7] sc1
	s_mov_b64 s[14:15], 0
	s_waitcnt vmcnt(0)
	v_cmp_lt_u32_e32 vcc, v1, v0
	s_and_saveexec_b64 s[12:13], vcc
	s_cbranch_execz .LBB0_1307
	s_add_u32 s10, s0, 0x200
	s_addc_u32 s11, s1, 0
	s_mov_b32 s25, 1
	s_branch .LBB0_1298

; __device__ __forceinline__ unsigned xb_ld(unsigned* p)              { return __hip_atomic_load(p, __ATOMIC_RELAXED, __HIP_MEMORY_SCOPE_AGENT); }
; #define XB_SPIN(cond, bar) do { unsigned _sp = 0; while (cond) { __builtin_amdgcn_s_sleep(1); \
;     if ((++_sp & 255u) == 0u) { if (xb_ld(&(bar)[XB_TMO])) break; if (_sp > XB_SPIN_CAP) { atomicAdd(&(bar)[XB_TMO], 1u); break; } } } } while (0)
; __device__ __forceinline__ void xcd_barrier_local(const XcdBarrier& b) {
;     ...
;         else XB_SPIN(xb_ld(&bar[XB_XSUB(b.x)]) < target, bar);
;         __builtin_amdgcn_fence(__ATOMIC_ACQUIRE, "agent");
;         asm volatile("s_waitcnt vmcnt(0)" ::: "memory");
;     }
.LBB0_1310:
	s_or_b64 exec, exec, s[0:1]
	s_waitcnt vmcnt(0)
	s_waitcnt vmcnt(0)

; __device__ __forceinline__ unsigned xb_ld(unsigned* p)              { return __hip_atomic_load(p, __ATOMIC_RELAXED, __HIP_MEMORY_SCOPE_AGENT); }
; __device__ __forceinline__ unsigned xb_add(unsigned* p, unsigned v) { return __hip_atomic_fetch_add(p, v, __ATOMIC_RELAXED, __HIP_MEMORY_SCOPE_AGENT); }
; #define XB_SPIN(cond, bar) do { unsigned _sp = 0; while (cond) { __builtin_amdgcn_s_sleep(1); \
;     if ((++_sp & 255u) == 0u) { if (xb_ld(&(bar)[XB_TMO])) break; if (_sp > XB_SPIN_CAP) { atomicAdd(&(bar)[XB_TMO], 1u); break; } } } } while (0)
; __device__ __forceinline__ void xcd_barrier_local(const XcdBarrier& b) {
;     ...
;         __builtin_amdgcn_s_waitcnt(0);
;         const unsigned nloc = b.st[0] ? b.st[0] : 1u;
;         const unsigned old = xb_add(&bar[XB_XSUB(b.x)], 1u);
;         const unsigned target = (old / nloc + 1u) * nloc;
;         if (old + 1u == target) (void)xb_add(&bar[XB_XGEN(b.x)], 1u);
;         else XB_SPIN(xb_ld(&bar[XB_XSUB(b.x)]) < target, bar);
.LBB0_1675:
	s_or_b64 exec, exec, s[8:9]
	buffer_inv sc1
	s_waitcnt vmcnt(0)
	v_readfirstlane_b32 s6, v2
	s_waitcnt lgkmcnt(0)
	v_cvt_f32_u32_e32 v2, v0
	v_sub_u32_e32 v3, 0, v0
	v_add_u32_e32 v1, s6, v1
	s_mov_b64 s[10:11], 0
	v_rcp_iflag_f32_e32 v2, v2
	s_nop 0
	v_mul_f32_e32 v2, 0x4f7ffffe, v2
	v_cvt_u32_f32_e32 v2, v2
	v_mul_lo_u32 v3, v3, v2
	v_mul_hi_u32 v3, v2, v3
	v_add_u32_e32 v2, v2, v3
	v_mul_hi_u32 v2, v1, v2
	v_mul_lo_u32 v3, v2, v0
	v_sub_u32_e32 v3, v1, v3
	v_cmp_ge_u32_e32 vcc, v3, v0
	v_add_u32_e32 v4, 1, v2
	v_add_u32_e32 v1, 1, v1
	v_cndmask_b32_e32 v2, v2, v4, vcc
	v_sub_u32_e32 v4, v3, v0
	v_cndmask_b32_e32 v3, v3, v4, vcc
	v_cmp_ge_u32_e32 vcc, v3, v0
	v_add_u32_e32 v3, 1, v2
	s_nop 0
	v_cndmask_b32_e32 v2, v2, v3, vcc
	v_mul_lo_u32 v2, v0, v2
	v_add_u32_e32 v0, v2, v0
	v_cmp_ne_u32_e32 vcc, v1, v0
	s_and_saveexec_b64 s[6:7], vcc
	s_xor_b64 s[6:7], exec, s[6:7]
	s_cbranch_execz .LBB0_1685
	global_load_dword v1, v201, s[4:5] sc1
	s_mov_b64 s[12:13], 0
	s_waitcnt vmcnt(0)
	v_cmp_lt_u32_e32 vcc, v1, v0
	s_and_saveexec_b64 s[10:11], vcc
	s_cbranch_execz .LBB0_1688
	s_add_u32 s8, s0, 0x200
	s_addc_u32 s9, s1, 0
	s_mov_b32 s23, 1
	s_branch .LBB0_1679

; __device__ __forceinline__ unsigned xb_ld(unsigned* p)              { return __hip_atomic_load(p, __ATOMIC_RELAXED, __HIP_MEMORY_SCOPE_AGENT); }
; __device__ __forceinline__ unsigned xb_add(unsigned* p, unsigned v) { return __hip_atomic_fetch_add(p, v, __ATOMIC_RELAXED, __HIP_MEMORY_SCOPE_AGENT); }
; #define XB_SPIN(cond, bar) do { unsigned _sp = 0; while (cond) { __builtin_amdgcn_s_sleep(1); \
;     if ((++_sp & 255u) == 0u) { if (xb_ld(&(bar)[XB_TMO])) break; if (_sp > XB_SPIN_CAP) { atomicAdd(&(bar)[XB_TMO], 1u); break; } } } } while (0)
; __device__ __forceinline__ void xcd_barrier_local(const XcdBarrier& b) {
;     ...
;         __builtin_amdgcn_s_waitcnt(0);
;         const unsigned nloc = b.st[0] ? b.st[0] : 1u;
;         const unsigned old = xb_add(&bar[XB_XSUB(b.x)], 1u);
;         const unsigned target = (old / nloc + 1u) * nloc;
;         if (old + 1u == target) (void)xb_add(&bar[XB_XGEN(b.x)], 1u);
;         else XB_SPIN(xb_ld(&bar[XB_XSUB(b.x)]) < target, bar);
.LBB0_1815:
	s_or_b64 exec, exec, s[12:13]
	buffer_inv sc1
	s_waitcnt vmcnt(0)
	v_readfirstlane_b32 s10, v2
	s_waitcnt lgkmcnt(0)
	v_cvt_f32_u32_e32 v2, v0
	v_sub_u32_e32 v3, 0, v0
	v_add_u32_e32 v1, s10, v1
	s_mov_b64 s[14:15], 0
	v_rcp_iflag_f32_e32 v2, v2
	s_nop 0
	v_mul_f32_e32 v2, 0x4f7ffffe, v2
	v_cvt_u32_f32_e32 v2, v2
	v_mul_lo_u32 v3, v3, v2
	v_mul_hi_u32 v3, v2, v3
	v_add_u32_e32 v2, v2, v3
	v_mul_hi_u32 v2, v1, v2
	v_mul_lo_u32 v3, v2, v0
	v_sub_u32_e32 v3, v1, v3
	v_cmp_ge_u32_e32 vcc, v3, v0
	v_add_u32_e32 v4, 1, v2
	v_add_u32_e32 v1, 1, v1
	v_cndmask_b32_e32 v2, v2, v4, vcc
	v_sub_u32_e32 v4, v3, v0
	v_cndmask_b32_e32 v3, v3, v4, vcc
	v_cmp_ge_u32_e32 vcc, v3, v0
	v_add_u32_e32 v3, 1, v2
	s_nop 0
	v_cndmask_b32_e32 v2, v2, v3, vcc
	v_mul_lo_u32 v2, v0, v2
	v_add_u32_e32 v0, v2, v0
	v_cmp_ne_u32_e32 vcc, v1, v0
	s_and_saveexec_b64 s[10:11], vcc
	s_xor_b64 s[10:11], exec, s[10:11]
	s_cbranch_execz .LBB0_1825
	global_load_dword v1, v201, s[6:7] sc1
	s_mov_b64 s[16:17], 0
	s_waitcnt vmcnt(0)
	v_cmp_lt_u32_e32 vcc, v1, v0
	s_and_saveexec_b64 s[14:15], vcc
	s_cbranch_execz .LBB0_1828
	s_add_u32 s12, s0, 0x200
	s_addc_u32 s13, s1, 0
	s_mov_b32 s27, 1
	s_branch .LBB0_1819

; __device__ __forceinline__ unsigned xb_ld(unsigned* p)              { return __hip_atomic_load(p, __ATOMIC_RELAXED, __HIP_MEMORY_SCOPE_AGENT); }
; __device__ __forceinline__ unsigned xb_add(unsigned* p, unsigned v) { return __hip_atomic_fetch_add(p, v, __ATOMIC_RELAXED, __HIP_MEMORY_SCOPE_AGENT); }
; #define XB_SPIN(cond, bar) do { unsigned _sp = 0; while (cond) { __builtin_amdgcn_s_sleep(1); \
;     if ((++_sp & 255u) == 0u) { if (xb_ld(&(bar)[XB_TMO])) break; if (_sp > XB_SPIN_CAP) { atomicAdd(&(bar)[XB_TMO], 1u); break; } } } } while (0)
; __device__ __forceinline__ void xcd_barrier_local(const XcdBarrier& b) {
;     ...
;         __builtin_amdgcn_s_waitcnt(0);
;         const unsigned nloc = b.st[0] ? b.st[0] : 1u;
;         const unsigned old = xb_add(&bar[XB_XSUB(b.x)], 1u);
;         const unsigned target = (old / nloc + 1u) * nloc;
;         if (old + 1u == target) (void)xb_add(&bar[XB_XGEN(b.x)], 1u);
;         else XB_SPIN(xb_ld(&bar[XB_XSUB(b.x)]) < target, bar);
.LBB0_2335:
	s_or_b64 exec, exec, s[12:13]
	buffer_inv sc1
	s_waitcnt vmcnt(0)
	v_readfirstlane_b32 s10, v2
	s_waitcnt lgkmcnt(0)
	v_cvt_f32_u32_e32 v2, v0
	v_sub_u32_e32 v3, 0, v0
	v_add_u32_e32 v1, s10, v1
	s_mov_b64 s[14:15], 0
	v_rcp_iflag_f32_e32 v2, v2
	s_nop 0
	v_mul_f32_e32 v2, 0x4f7ffffe, v2
	v_cvt_u32_f32_e32 v2, v2
	v_mul_lo_u32 v3, v3, v2
	v_mul_hi_u32 v3, v2, v3
	v_add_u32_e32 v2, v2, v3
	v_mul_hi_u32 v2, v1, v2
	v_mul_lo_u32 v3, v2, v0
	v_sub_u32_e32 v3, v1, v3
	v_cmp_ge_u32_e32 vcc, v3, v0
	v_add_u32_e32 v4, 1, v2
	v_add_u32_e32 v1, 1, v1
	v_cndmask_b32_e32 v2, v2, v4, vcc
	v_sub_u32_e32 v4, v3, v0
	v_cndmask_b32_e32 v3, v3, v4, vcc
	v_cmp_ge_u32_e32 vcc, v3, v0
	v_add_u32_e32 v3, 1, v2
	s_nop 0
	v_cndmask_b32_e32 v2, v2, v3, vcc
	v_mul_lo_u32 v2, v0, v2
	v_add_u32_e32 v0, v2, v0
	v_cmp_ne_u32_e32 vcc, v1, v0
	s_and_saveexec_b64 s[10:11], vcc
	s_xor_b64 s[10:11], exec, s[10:11]
	s_cbranch_execz .LBB0_2345
	global_load_dword v1, v201, s[4:5] sc1
	s_mov_b64 s[16:17], 0
	s_waitcnt vmcnt(0)
	v_cmp_lt_u32_e32 vcc, v1, v0
	s_and_saveexec_b64 s[14:15], vcc
	s_cbranch_execz .LBB0_2348
	s_add_u32 s12, s0, 0x200
	s_addc_u32 s13, s1, 0
	s_mov_b32 s27, 1
	s_branch .LBB0_2339
